# static s_setprio 1 for the leading wave group in the in-proj, out-proj, MLP1 and MLP2 GEMM loops (reset at the epilogues)
# speedup vs baseline: 1.0037x; 1.0037x over previous
; DEVI void gemm16s(f32x4 (&acc)[4][8], const GUnit& cur, const GUnit& nxt, bool has_next, bool first, int& stg, bfu* lds) {
;     ...
; #pragma unroll 1
;     for (int kt = 0; kt < nkt; ++kt) {
;       G16_HEAD()
;       bf16x8 tf0[8], wf0[4];
;       G16_RD(tf0, wf0, 0)
;       ISSUE16(Ai, Bi, sAi, sBi, vAi, vBi, tk, st ^ 1);
;       G16_MM(tf0, wf0)
;       bf16x8 tf1[8], wf1[4];
;       G16_RD(tf1, wf1, 1)
;       G16_MM(tf1, wf1)
;       __builtin_amdgcn_sched_group_barrier(0x100, 12, 0);
; #pragma unroll
;       for (int i = 0; i < 8; ++i) {
;         __builtin_amdgcn_sched_group_barrier(0x008, 2, 0);
;         __builtin_amdgcn_sched_group_barrier(0x020, 1, 0);
;       }
; #pragma unroll
;       for (int i = 0; i < 12; ++i) {
;         __builtin_amdgcn_sched_group_barrier(0x008, 1, 0);
;         __builtin_amdgcn_sched_group_barrier(0x100, 1, 0);
;       }
;       __builtin_amdgcn_sched_group_barrier(0x008, 36, 0);
;       st ^= 1;
.LBB0_34:
	s_setprio 1
	s_add_i32 s20, s23, 1
	s_cmp_gt_u32 s23, 62
	s_cselect_b64 s[36:37], -1, 0
	s_and_b64 s[60:61], s[36:37], exec
	s_cselect_b32 s30, s59, s20
	s_and_b64 s[36:37], s[40:41], s[36:37]
	s_and_b64 s[60:61], s[36:37], exec
	s_cselect_b32 s61, s49, s45
	s_cselect_b32 s60, s29, s44
	s_lshl_b32 s23, s56, 16
	s_addk_i32 s23, 0xc20
	v_add_u32_e32 v158, s23, v185
	s_waitcnt vmcnt(0)
	v_add3_u32 v154, v158, v187, v188
	v_add3_u32 v158, v158, v189, v188
	s_waitcnt lgkmcnt(0)
	s_barrier
; DEVI void gemm16s(f32x4 (&acc)[4][8], const GUnit& cur, const GUnit& nxt, bool has_next, bool first, int& stg, bfu* lds) {
;     ...
; #pragma unroll 1
;     for (int kt = 0; kt < nkt; ++kt) {
;       G16_HEAD()
;       bf16x8 tf0[8], wf0[4];
;       G16_RD(tf0, wf0, 0)
;       ISSUE16(Ai, Bi, sAi, sBi, vAi, vBi, tk, st ^ 1);
;       G16_MM(tf0, wf0)
;       bf16x8 tf1[8], wf1[4];
;       G16_RD(tf1, wf1, 1)
;       G16_MM(tf1, wf1)
;       __builtin_amdgcn_sched_group_barrier(0x100, 12, 0);
; #pragma unroll
;       for (int i = 0; i < 8; ++i) {
;         __builtin_amdgcn_sched_group_barrier(0x008, 2, 0);
;         __builtin_amdgcn_sched_group_barrier(0x020, 1, 0);
;       }
; #pragma unroll
;       for (int i = 0; i < 12; ++i) {
;         __builtin_amdgcn_sched_group_barrier(0x008, 1, 0);
;         __builtin_amdgcn_sched_group_barrier(0x100, 1, 0);
;       }
;       __builtin_amdgcn_sched_group_barrier(0x008, 36, 0);
;       st ^= 1;
;     }
	ds_read_b128 v[174:177], v158 offset:32768
	s_and_b64 s[36:37], s[36:37], exec
	s_cselect_b32 s62, s58, s51
	s_cselect_b32 s63, s57, s50
	s_xor_b32 s56, s56, 1
	ds_read_b128 v[126:129], v154
	ds_read_b128 v[130:133], v154 offset:2048
	s_lshl_b32 s36, s56, 16
	ds_read_b128 v[134:137], v154 offset:4096
	ds_read_b128 v[138:141], v154 offset:6144
	s_add_i32 s64, s28, s36
	s_lshl_b64 s[36:37], s[30:31], 7
	ds_read_b128 v[142:145], v154 offset:8192
	ds_read_b128 v[146:149], v154 offset:10240
	ds_read_b128 v[170:173], v158 offset:34816
	s_add_u32 s60, s60, s36
	s_addc_u32 s61, s61, s37
	v_lshl_add_u64 v[190:191], s[60:61], 0, v[0:1]
	s_mov_b32 m0, s64
	ds_read_b128 v[150:153], v154 offset:12288
	ds_read_b128 v[154:157], v154 offset:14336
	ds_read_b128 v[166:169], v158 offset:36864
	ds_read_b128 v[158:161], v158 offset:38912
	v_lshl_add_u64 v[192:193], v[190:191], 0, s[66:67]
	s_waitcnt lgkmcnt(0)
	v_mfma_f32_16x16x32_bf16 v[162:165], v[174:177], v[126:129], v[162:165]
	v_mfma_f32_16x16x32_bf16 v[118:121], v[174:177], v[130:133], v[118:121]
	global_load_lds_dwordx4 v[190:191], off
	s_add_i32 m0, s64, 0x2000
	v_mfma_f32_16x16x32_bf16 v[98:101], v[174:177], v[134:137], v[98:101]
	v_mfma_f32_16x16x32_bf16 v[82:85], v[174:177], v[138:141], v[82:85]
	global_load_lds_dwordx4 v[192:193], off
	v_lshl_add_u64 v[192:193], v[190:191], 0, s[68:69]
	s_add_i32 m0, s64, 0x4000
	v_mfma_f32_16x16x32_bf16 v[66:69], v[174:177], v[142:145], v[66:69]
	v_lshl_add_u64 v[190:191], v[190:191], 0, s[70:71]
	v_mfma_f32_16x16x32_bf16 v[50:53], v[174:177], v[146:149], v[50:53]
	global_load_lds_dwordx4 v[192:193], off
	s_add_i32 m0, s64, 0x6000
	s_add_u32 s36, s63, s36
	s_addc_u32 s37, s62, s37
	v_mfma_f32_16x16x32_bf16 v[34:37], v[174:177], v[150:153], v[34:37]
	v_mfma_f32_16x16x32_bf16 v[14:17], v[174:177], v[154:157], v[14:17]
	global_load_lds_dwordx4 v[190:191], off
	v_lshl_add_u64 v[190:191], s[36:37], 0, v[0:1]
	s_add_i32 m0, s64, 0x8000
	v_lshl_add_u64 v[192:193], v[190:191], 0, s[66:67]
	v_mfma_f32_16x16x32_bf16 v[122:125], v[170:173], v[126:129], v[122:125]
	v_mfma_f32_16x16x32_bf16 v[106:109], v[170:173], v[130:133], v[106:109]
	global_load_lds_dwordx4 v[190:191], off
	s_add_i32 m0, s64, 0xa000
	v_mfma_f32_16x16x32_bf16 v[90:93], v[170:173], v[134:137], v[90:93]
	v_mfma_f32_16x16x32_bf16 v[74:77], v[170:173], v[138:141], v[74:77]
	global_load_lds_dwordx4 v[192:193], off
	v_lshl_add_u64 v[192:193], v[190:191], 0, s[68:69]
	s_add_i32 m0, s64, 0xc000
	v_lshl_add_u64 v[190:191], v[190:191], 0, s[70:71]
	v_mfma_f32_16x16x32_bf16 v[58:61], v[170:173], v[142:145], v[58:61]
	v_mfma_f32_16x16x32_bf16 v[42:45], v[170:173], v[146:149], v[42:45]
	global_load_lds_dwordx4 v[192:193], off
	s_add_i32 m0, s64, 0xe000
	v_mfma_f32_16x16x32_bf16 v[26:29], v[170:173], v[150:153], v[26:29]
	s_cmp_eq_u32 s20, 64
	v_mfma_f32_16x16x32_bf16 v[10:13], v[170:173], v[154:157], v[10:13]
	global_load_lds_dwordx4 v[190:191], off
	v_mfma_f32_16x16x32_bf16 v[114:117], v[166:169], v[126:129], v[114:117]
	v_mfma_f32_16x16x32_bf16 v[102:105], v[166:169], v[130:133], v[102:105]
	v_mfma_f32_16x16x32_bf16 v[110:113], v[158:161], v[126:129], v[110:113]
	v_mfma_f32_16x16x32_bf16 v[94:97], v[158:161], v[130:133], v[94:97]
	v_mfma_f32_16x16x32_bf16 v[78:81], v[158:161], v[134:137], v[78:81]
	v_mfma_f32_16x16x32_bf16 v[62:65], v[158:161], v[138:141], v[62:65]
	v_mfma_f32_16x16x32_bf16 v[46:49], v[158:161], v[142:145], v[46:49]
	v_mfma_f32_16x16x32_bf16 v[30:33], v[158:161], v[146:149], v[30:33]
	v_mfma_f32_16x16x32_bf16 v[18:21], v[158:161], v[150:153], v[18:21]
	v_mfma_f32_16x16x32_bf16 v[2:5], v[158:161], v[154:157], v[2:5]
	v_add_u32_e32 v158, s23, v186
	v_add3_u32 v174, v158, v189, v188
	ds_read_b128 v[170:173], v174 offset:36864
	v_mfma_f32_16x16x32_bf16 v[86:89], v[166:169], v[134:137], v[86:89]
	s_mov_b32 s23, s20
	v_mfma_f32_16x16x32_bf16 v[70:73], v[166:169], v[138:141], v[70:73]
	v_mfma_f32_16x16x32_bf16 v[54:57], v[166:169], v[142:145], v[54:57]
	v_mfma_f32_16x16x32_bf16 v[38:41], v[166:169], v[146:149], v[38:41]
	v_mfma_f32_16x16x32_bf16 v[22:25], v[166:169], v[150:153], v[22:25]
	v_mfma_f32_16x16x32_bf16 v[6:9], v[166:169], v[154:157], v[6:9]
	v_add3_u32 v154, v158, v187, v188
	ds_read_b128 v[166:169], v174 offset:34816
	ds_read_b128 v[158:161], v174 offset:32768
	ds_read_b128 v[174:177], v174 offset:38912
	ds_read_b128 v[150:153], v154 offset:12288
	ds_read_b128 v[146:149], v154 offset:10240
	ds_read_b128 v[142:145], v154 offset:8192
	ds_read_b128 v[138:141], v154 offset:6144
	ds_read_b128 v[134:137], v154 offset:4096
	ds_read_b128 v[130:133], v154 offset:2048
	ds_read_b128 v[126:129], v154
	ds_read_b128 v[154:157], v154 offset:14336
	s_waitcnt lgkmcnt(0)
	v_mfma_f32_16x16x32_bf16 v[162:165], v[158:161], v[126:129], v[162:165]
	v_mfma_f32_16x16x32_bf16 v[118:121], v[158:161], v[130:133], v[118:121]
	v_mfma_f32_16x16x32_bf16 v[98:101], v[158:161], v[134:137], v[98:101]
	v_mfma_f32_16x16x32_bf16 v[82:85], v[158:161], v[138:141], v[82:85]
	v_mfma_f32_16x16x32_bf16 v[66:69], v[158:161], v[142:145], v[66:69]
	v_mfma_f32_16x16x32_bf16 v[50:53], v[158:161], v[146:149], v[50:53]
	v_mfma_f32_16x16x32_bf16 v[34:37], v[158:161], v[150:153], v[34:37]
	v_mfma_f32_16x16x32_bf16 v[14:17], v[158:161], v[154:157], v[14:17]
	v_mfma_f32_16x16x32_bf16 v[122:125], v[166:169], v[126:129], v[122:125]
	v_mfma_f32_16x16x32_bf16 v[106:109], v[166:169], v[130:133], v[106:109]
	v_mfma_f32_16x16x32_bf16 v[90:93], v[166:169], v[134:137], v[90:93]
	v_mfma_f32_16x16x32_bf16 v[74:77], v[166:169], v[138:141], v[74:77]
	v_mfma_f32_16x16x32_bf16 v[58:61], v[166:169], v[142:145], v[58:61]
	v_mfma_f32_16x16x32_bf16 v[42:45], v[166:169], v[146:149], v[42:45]
	v_mfma_f32_16x16x32_bf16 v[26:29], v[166:169], v[150:153], v[26:29]
	v_mfma_f32_16x16x32_bf16 v[10:13], v[166:169], v[154:157], v[10:13]
	v_mfma_f32_16x16x32_bf16 v[114:117], v[170:173], v[126:129], v[114:117]
	v_mfma_f32_16x16x32_bf16 v[102:105], v[170:173], v[130:133], v[102:105]
	v_mfma_f32_16x16x32_bf16 v[86:89], v[170:173], v[134:137], v[86:89]
	v_mfma_f32_16x16x32_bf16 v[70:73], v[170:173], v[138:141], v[70:73]
	v_mfma_f32_16x16x32_bf16 v[54:57], v[170:173], v[142:145], v[54:57]
	v_mfma_f32_16x16x32_bf16 v[38:41], v[170:173], v[146:149], v[38:41]
	v_mfma_f32_16x16x32_bf16 v[22:25], v[170:173], v[150:153], v[22:25]
	v_mfma_f32_16x16x32_bf16 v[6:9], v[170:173], v[154:157], v[6:9]
	v_mfma_f32_16x16x32_bf16 v[110:113], v[174:177], v[126:129], v[110:113]
	v_mfma_f32_16x16x32_bf16 v[94:97], v[174:177], v[130:133], v[94:97]
	v_mfma_f32_16x16x32_bf16 v[78:81], v[174:177], v[134:137], v[78:81]
	v_mfma_f32_16x16x32_bf16 v[62:65], v[174:177], v[138:141], v[62:65]
	v_mfma_f32_16x16x32_bf16 v[46:49], v[174:177], v[142:145], v[46:49]
	v_mfma_f32_16x16x32_bf16 v[30:33], v[174:177], v[146:149], v[30:33]
	v_mfma_f32_16x16x32_bf16 v[18:21], v[174:177], v[150:153], v[18:21]
	v_mfma_f32_16x16x32_bf16 v[2:5], v[174:177], v[154:157], v[2:5]
	s_cbranch_scc0 .LBB0_34
	s_mov_b32 s20, s56

; DEVI void gemm16s(f32x4 (&acc)[4][8], const GUnit& cur, const GUnit& nxt, bool has_next, bool first, int& stg, bfu* lds) {
;     ...
; #pragma unroll 1
;     for (int kt = 0; kt < nkt; ++kt) {
;       G16_HEAD()
;       bf16x8 tf0[8], wf0[4];
;       G16_RD(tf0, wf0, 0)
;       ISSUE16(Ai, Bi, sAi, sBi, vAi, vBi, tk, st ^ 1);
;       G16_MM(tf0, wf0)
;       bf16x8 tf1[8], wf1[4];
;       G16_RD(tf1, wf1, 1)
;       G16_MM(tf1, wf1)
;       __builtin_amdgcn_sched_group_barrier(0x100, 12, 0);
; #pragma unroll
;       for (int i = 0; i < 8; ++i) {
;         __builtin_amdgcn_sched_group_barrier(0x008, 2, 0);
;         __builtin_amdgcn_sched_group_barrier(0x020, 1, 0);
;       }
; #pragma unroll
;       for (int i = 0; i < 12; ++i) {
;         __builtin_amdgcn_sched_group_barrier(0x008, 1, 0);
;         __builtin_amdgcn_sched_group_barrier(0x100, 1, 0);
;       }
;       __builtin_amdgcn_sched_group_barrier(0x008, 36, 0);
;       st ^= 1;
.LBB0_220:
	s_setprio 1
	s_add_i32 s20, s23, 1
	s_cmp_gt_u32 s23, 14
	s_cselect_b64 s[36:37], -1, 0
	s_and_b64 s[52:53], s[36:37], exec
	s_cselect_b32 s30, s51, s20
	s_and_b64 s[36:37], s[4:5], s[36:37]
	s_and_b64 s[52:53], s[36:37], exec
	s_cselect_b32 s53, s48, s39
	s_cselect_b32 s52, s47, s38
	s_lshl_b32 s23, s43, 16
	s_addk_i32 s23, 0xc20
	v_add_u32_e32 v154, s23, v185
	s_waitcnt vmcnt(0)
	v_add3_u32 v146, v154, v187, v188
	v_add3_u32 v154, v154, v189, v188
	s_waitcnt lgkmcnt(0)
	s_barrier
; DEVI void gemm16s(f32x4 (&acc)[4][8], const GUnit& cur, const GUnit& nxt, bool has_next, bool first, int& stg, bfu* lds) {
;     ...
; #pragma unroll 1
;     for (int kt = 0; kt < nkt; ++kt) {
;       G16_HEAD()
;       bf16x8 tf0[8], wf0[4];
;       G16_RD(tf0, wf0, 0)
;       ISSUE16(Ai, Bi, sAi, sBi, vAi, vBi, tk, st ^ 1);
;       G16_MM(tf0, wf0)
;       bf16x8 tf1[8], wf1[4];
;       G16_RD(tf1, wf1, 1)
;       G16_MM(tf1, wf1)
;       __builtin_amdgcn_sched_group_barrier(0x100, 12, 0);
; #pragma unroll
;       for (int i = 0; i < 8; ++i) {
;         __builtin_amdgcn_sched_group_barrier(0x008, 2, 0);
;         __builtin_amdgcn_sched_group_barrier(0x020, 1, 0);
;       }
; #pragma unroll
;       for (int i = 0; i < 12; ++i) {
;         __builtin_amdgcn_sched_group_barrier(0x008, 1, 0);
;         __builtin_amdgcn_sched_group_barrier(0x100, 1, 0);
;       }
;       __builtin_amdgcn_sched_group_barrier(0x008, 36, 0);
;       st ^= 1;
;     }
	ds_read_b128 v[174:177], v154 offset:32768
	s_and_b64 s[36:37], s[36:37], exec
	s_cselect_b32 s54, s50, s41
	s_cselect_b32 s55, s49, s40
	s_xor_b32 s43, s43, 1
	ds_read_b128 v[114:117], v146
	ds_read_b128 v[118:121], v146 offset:2048
	s_lshl_b32 s36, s43, 16
	ds_read_b128 v[122:125], v146 offset:4096
	ds_read_b128 v[126:129], v146 offset:6144
	s_add_i32 s56, s46, s36
	s_lshl_b64 s[36:37], s[30:31], 7
	ds_read_b128 v[134:137], v146 offset:8192
	ds_read_b128 v[138:141], v146 offset:10240
	ds_read_b128 v[170:173], v154 offset:34816
	s_add_u32 s52, s52, s36
	s_addc_u32 s53, s53, s37
	v_lshl_add_u64 v[190:191], s[52:53], 0, v[0:1]
	s_mov_b32 m0, s56
	ds_read_b128 v[142:145], v146 offset:12288
	ds_read_b128 v[146:149], v146 offset:14336
	ds_read_b128 v[166:169], v154 offset:36864
	ds_read_b128 v[154:157], v154 offset:38912
	v_lshl_add_u64 v[192:193], v[190:191], 0, s[14:15]
	s_waitcnt lgkmcnt(0)
	v_mfma_f32_16x16x32_bf16 v[162:165], v[174:177], v[114:117], v[162:165]
	v_mfma_f32_16x16x32_bf16 v[158:161], v[174:177], v[118:121], v[158:161]
	global_load_lds_dwordx4 v[190:191], off
	s_add_i32 m0, s56, 0x2000
	v_mfma_f32_16x16x32_bf16 v[150:153], v[174:177], v[122:125], v[150:153]
	v_mfma_f32_16x16x32_bf16 v[130:133], v[174:177], v[126:129], v[130:133]
	global_load_lds_dwordx4 v[192:193], off
	v_lshl_add_u64 v[192:193], v[190:191], 0, s[8:9]
	s_add_i32 m0, s56, 0x4000
	v_mfma_f32_16x16x32_bf16 v[110:113], v[174:177], v[134:137], v[110:113]
	v_lshl_add_u64 v[190:191], v[190:191], 0, s[34:35]
	v_mfma_f32_16x16x32_bf16 v[106:109], v[174:177], v[138:141], v[106:109]
	global_load_lds_dwordx4 v[192:193], off
	s_add_i32 m0, s56, 0x6000
	s_add_u32 s36, s55, s36
	s_addc_u32 s37, s54, s37
	v_mfma_f32_16x16x32_bf16 v[102:105], v[174:177], v[142:145], v[102:105]
	v_mfma_f32_16x16x32_bf16 v[98:101], v[174:177], v[146:149], v[98:101]
	global_load_lds_dwordx4 v[190:191], off
	v_lshl_add_u64 v[190:191], s[36:37], 0, v[0:1]
	s_add_i32 m0, s56, 0x8000
	v_lshl_add_u64 v[192:193], v[190:191], 0, s[14:15]
	v_mfma_f32_16x16x32_bf16 v[94:97], v[170:173], v[114:117], v[94:97]
	v_mfma_f32_16x16x32_bf16 v[90:93], v[170:173], v[118:121], v[90:93]
	global_load_lds_dwordx4 v[190:191], off
	s_add_i32 m0, s56, 0xa000
	v_mfma_f32_16x16x32_bf16 v[86:89], v[170:173], v[122:125], v[86:89]
	v_mfma_f32_16x16x32_bf16 v[82:85], v[170:173], v[126:129], v[82:85]
	global_load_lds_dwordx4 v[192:193], off
	v_lshl_add_u64 v[192:193], v[190:191], 0, s[8:9]
	s_add_i32 m0, s56, 0xc000
	v_lshl_add_u64 v[190:191], v[190:191], 0, s[34:35]
	v_mfma_f32_16x16x32_bf16 v[78:81], v[170:173], v[134:137], v[78:81]
	v_mfma_f32_16x16x32_bf16 v[74:77], v[170:173], v[138:141], v[74:77]
	global_load_lds_dwordx4 v[192:193], off
	s_add_i32 m0, s56, 0xe000
	v_mfma_f32_16x16x32_bf16 v[70:73], v[170:173], v[142:145], v[70:73]
	s_cmp_eq_u32 s20, 16
	v_mfma_f32_16x16x32_bf16 v[66:69], v[170:173], v[146:149], v[66:69]
	global_load_lds_dwordx4 v[190:191], off
	v_mfma_f32_16x16x32_bf16 v[62:65], v[166:169], v[114:117], v[62:65]
	v_mfma_f32_16x16x32_bf16 v[58:61], v[166:169], v[118:121], v[58:61]
	v_mfma_f32_16x16x32_bf16 v[30:33], v[154:157], v[114:117], v[30:33]
	v_mfma_f32_16x16x32_bf16 v[26:29], v[154:157], v[118:121], v[26:29]
	v_mfma_f32_16x16x32_bf16 v[22:25], v[154:157], v[122:125], v[22:25]
	v_mfma_f32_16x16x32_bf16 v[18:21], v[154:157], v[126:129], v[18:21]
	v_mfma_f32_16x16x32_bf16 v[14:17], v[154:157], v[134:137], v[14:17]
	v_mfma_f32_16x16x32_bf16 v[10:13], v[154:157], v[138:141], v[10:13]
	v_mfma_f32_16x16x32_bf16 v[6:9], v[154:157], v[142:145], v[6:9]
	v_mfma_f32_16x16x32_bf16 v[2:5], v[154:157], v[146:149], v[2:5]
	v_add_u32_e32 v154, s23, v186
	v_add3_u32 v174, v154, v189, v188
	ds_read_b128 v[170:173], v174 offset:36864
	v_mfma_f32_16x16x32_bf16 v[54:57], v[166:169], v[122:125], v[54:57]
	s_mov_b32 s23, s20
	v_mfma_f32_16x16x32_bf16 v[50:53], v[166:169], v[126:129], v[50:53]
	v_mfma_f32_16x16x32_bf16 v[46:49], v[166:169], v[134:137], v[46:49]
	v_mfma_f32_16x16x32_bf16 v[42:45], v[166:169], v[138:141], v[42:45]
	v_mfma_f32_16x16x32_bf16 v[38:41], v[166:169], v[142:145], v[38:41]
	v_mfma_f32_16x16x32_bf16 v[34:37], v[166:169], v[146:149], v[34:37]
	v_add3_u32 v146, v154, v187, v188
	ds_read_b128 v[166:169], v174 offset:34816
	ds_read_b128 v[154:157], v174 offset:32768
	ds_read_b128 v[174:177], v174 offset:38912
	ds_read_b128 v[142:145], v146 offset:12288
	ds_read_b128 v[138:141], v146 offset:10240
	ds_read_b128 v[134:137], v146 offset:8192
	ds_read_b128 v[126:129], v146 offset:6144
	ds_read_b128 v[122:125], v146 offset:4096
	ds_read_b128 v[118:121], v146 offset:2048
	ds_read_b128 v[114:117], v146
	ds_read_b128 v[146:149], v146 offset:14336
	s_waitcnt lgkmcnt(0)
	v_mfma_f32_16x16x32_bf16 v[162:165], v[154:157], v[114:117], v[162:165]
	v_mfma_f32_16x16x32_bf16 v[158:161], v[154:157], v[118:121], v[158:161]
	v_mfma_f32_16x16x32_bf16 v[150:153], v[154:157], v[122:125], v[150:153]
	v_mfma_f32_16x16x32_bf16 v[130:133], v[154:157], v[126:129], v[130:133]
	v_mfma_f32_16x16x32_bf16 v[110:113], v[154:157], v[134:137], v[110:113]
	v_mfma_f32_16x16x32_bf16 v[106:109], v[154:157], v[138:141], v[106:109]
	v_mfma_f32_16x16x32_bf16 v[102:105], v[154:157], v[142:145], v[102:105]
	v_mfma_f32_16x16x32_bf16 v[98:101], v[154:157], v[146:149], v[98:101]
	v_mfma_f32_16x16x32_bf16 v[94:97], v[166:169], v[114:117], v[94:97]
	v_mfma_f32_16x16x32_bf16 v[90:93], v[166:169], v[118:121], v[90:93]
	v_mfma_f32_16x16x32_bf16 v[86:89], v[166:169], v[122:125], v[86:89]
	v_mfma_f32_16x16x32_bf16 v[82:85], v[166:169], v[126:129], v[82:85]
	v_mfma_f32_16x16x32_bf16 v[78:81], v[166:169], v[134:137], v[78:81]
	v_mfma_f32_16x16x32_bf16 v[74:77], v[166:169], v[138:141], v[74:77]
	v_mfma_f32_16x16x32_bf16 v[70:73], v[166:169], v[142:145], v[70:73]
	v_mfma_f32_16x16x32_bf16 v[66:69], v[166:169], v[146:149], v[66:69]
	v_mfma_f32_16x16x32_bf16 v[62:65], v[170:173], v[114:117], v[62:65]
	v_mfma_f32_16x16x32_bf16 v[58:61], v[170:173], v[118:121], v[58:61]
	v_mfma_f32_16x16x32_bf16 v[54:57], v[170:173], v[122:125], v[54:57]
	v_mfma_f32_16x16x32_bf16 v[50:53], v[170:173], v[126:129], v[50:53]
	v_mfma_f32_16x16x32_bf16 v[46:49], v[170:173], v[134:137], v[46:49]
	v_mfma_f32_16x16x32_bf16 v[42:45], v[170:173], v[138:141], v[42:45]
	v_mfma_f32_16x16x32_bf16 v[38:41], v[170:173], v[142:145], v[38:41]
	v_mfma_f32_16x16x32_bf16 v[34:37], v[170:173], v[146:149], v[34:37]
	v_mfma_f32_16x16x32_bf16 v[30:33], v[174:177], v[114:117], v[30:33]
	v_mfma_f32_16x16x32_bf16 v[26:29], v[174:177], v[118:121], v[26:29]
	v_mfma_f32_16x16x32_bf16 v[22:25], v[174:177], v[122:125], v[22:25]
	v_mfma_f32_16x16x32_bf16 v[18:21], v[174:177], v[126:129], v[18:21]
	v_mfma_f32_16x16x32_bf16 v[14:17], v[174:177], v[134:137], v[14:17]
	v_mfma_f32_16x16x32_bf16 v[10:13], v[174:177], v[138:141], v[10:13]
	v_mfma_f32_16x16x32_bf16 v[6:9], v[174:177], v[142:145], v[6:9]
	v_mfma_f32_16x16x32_bf16 v[2:5], v[174:177], v[146:149], v[2:5]
	s_cbranch_scc0 .LBB0_220
	s_mov_b32 s20, s43
	s_mov_b32 s43, s20
	s_andn2_b64 vcc, exec, s[0:1]
	s_cbranch_vccnz .LBB0_204

; DEVI void gemm16s(f32x4 (&acc)[4][8], const GUnit& cur, const GUnit& nxt, bool has_next, bool first, int& stg, bfu* lds) {
;     ...
; #pragma unroll 1
;     for (int kt = 0; kt < nkt; ++kt) {
;       G16_HEAD()
;       bf16x8 tf0[8], wf0[4];
;       G16_RD(tf0, wf0, 0)
;       ISSUE16(Ai, Bi, sAi, sBi, vAi, vBi, tk, st ^ 1);
;       G16_MM(tf0, wf0)
;       bf16x8 tf1[8], wf1[4];
;       G16_RD(tf1, wf1, 1)
;       G16_MM(tf1, wf1)
;       __builtin_amdgcn_sched_group_barrier(0x100, 12, 0);
; #pragma unroll
;       for (int i = 0; i < 8; ++i) {
;         __builtin_amdgcn_sched_group_barrier(0x008, 2, 0);
;         __builtin_amdgcn_sched_group_barrier(0x020, 1, 0);
;       }
; #pragma unroll
;       for (int i = 0; i < 12; ++i) {
;         __builtin_amdgcn_sched_group_barrier(0x008, 1, 0);
;         __builtin_amdgcn_sched_group_barrier(0x100, 1, 0);
;       }
;       __builtin_amdgcn_sched_group_barrier(0x008, 36, 0);
;       st ^= 1;
;     }
.LBB0_245:
	s_setprio 1
	s_add_i32 s20, s23, 1
	s_cmp_gt_u32 s23, 14
	s_cselect_b64 s[36:37], -1, 0
	s_and_b64 s[58:59], s[36:37], exec
	s_cselect_b32 s30, s57, s20
	s_and_b64 s[36:37], s[40:41], s[36:37]
	s_and_b64 s[58:59], s[36:37], exec
	s_cselect_b32 s59, s43, s47
	s_cselect_b32 s58, s29, s46
	s_lshl_b32 s23, s54, 16
	s_addk_i32 s23, 0xc20
	v_add_u32_e32 v158, s23, v184
	s_waitcnt vmcnt(0)
	v_add3_u32 v154, v158, v186, v187
	v_add3_u32 v158, v158, v188, v187
	s_waitcnt lgkmcnt(0)
	s_barrier
	ds_read_b128 v[174:177], v158 offset:32768
	s_and_b64 s[36:37], s[36:37], exec
	s_cselect_b32 s60, s56, s49
	s_cselect_b32 s61, s55, s48
	s_xor_b32 s54, s54, 1
	ds_read_b128 v[126:129], v154
	ds_read_b128 v[130:133], v154 offset:2048
	s_lshl_b32 s36, s54, 16
	ds_read_b128 v[134:137], v154 offset:4096
	ds_read_b128 v[138:141], v154 offset:6144
	s_add_i32 s62, s28, s36
	s_lshl_b64 s[36:37], s[30:31], 7
	ds_read_b128 v[142:145], v154 offset:8192
	ds_read_b128 v[146:149], v154 offset:10240
	ds_read_b128 v[170:173], v158 offset:34816
	s_add_u32 s58, s58, s36
	s_addc_u32 s59, s59, s37
	v_lshl_add_u64 v[190:191], s[58:59], 0, v[0:1]
	s_mov_b32 m0, s62
	ds_read_b128 v[150:153], v154 offset:12288
	ds_read_b128 v[154:157], v154 offset:14336
	ds_read_b128 v[166:169], v158 offset:36864
	ds_read_b128 v[158:161], v158 offset:38912
	v_lshl_add_u64 v[192:193], v[190:191], 0, s[14:15]
	s_waitcnt lgkmcnt(0)
	v_mfma_f32_16x16x32_bf16 v[162:165], v[174:177], v[126:129], v[162:165]
	v_mfma_f32_16x16x32_bf16 v[114:117], v[174:177], v[130:133], v[114:117]
	global_load_lds_dwordx4 v[190:191], off
	s_add_i32 m0, s62, 0x2000
	v_mfma_f32_16x16x32_bf16 v[98:101], v[174:177], v[134:137], v[98:101]
	v_mfma_f32_16x16x32_bf16 v[82:85], v[174:177], v[138:141], v[82:85]
	global_load_lds_dwordx4 v[192:193], off
	v_lshl_add_u64 v[192:193], v[190:191], 0, s[8:9]
	s_add_i32 m0, s62, 0x4000
	v_mfma_f32_16x16x32_bf16 v[66:69], v[174:177], v[142:145], v[66:69]
	v_lshl_add_u64 v[190:191], v[190:191], 0, s[34:35]
	v_mfma_f32_16x16x32_bf16 v[50:53], v[174:177], v[146:149], v[50:53]
	global_load_lds_dwordx4 v[192:193], off
	s_add_i32 m0, s62, 0x6000
	s_add_u32 s36, s61, s36
	s_addc_u32 s37, s60, s37
	v_mfma_f32_16x16x32_bf16 v[34:37], v[174:177], v[150:153], v[34:37]
	v_mfma_f32_16x16x32_bf16 v[18:21], v[174:177], v[154:157], v[18:21]
	global_load_lds_dwordx4 v[190:191], off
	v_lshl_add_u64 v[190:191], s[36:37], 0, v[0:1]
	s_add_i32 m0, s62, 0x8000
	v_lshl_add_u64 v[192:193], v[190:191], 0, s[14:15]
	v_mfma_f32_16x16x32_bf16 v[122:125], v[170:173], v[126:129], v[122:125]
	v_mfma_f32_16x16x32_bf16 v[106:109], v[170:173], v[130:133], v[106:109]
	global_load_lds_dwordx4 v[190:191], off
	s_add_i32 m0, s62, 0xa000
	v_mfma_f32_16x16x32_bf16 v[90:93], v[170:173], v[134:137], v[90:93]
	v_mfma_f32_16x16x32_bf16 v[74:77], v[170:173], v[138:141], v[74:77]
	global_load_lds_dwordx4 v[192:193], off
	v_lshl_add_u64 v[192:193], v[190:191], 0, s[8:9]
	s_add_i32 m0, s62, 0xc000
	v_lshl_add_u64 v[190:191], v[190:191], 0, s[34:35]
	v_mfma_f32_16x16x32_bf16 v[58:61], v[170:173], v[142:145], v[58:61]
	v_mfma_f32_16x16x32_bf16 v[42:45], v[170:173], v[146:149], v[42:45]
	global_load_lds_dwordx4 v[192:193], off
	s_add_i32 m0, s62, 0xe000
	v_mfma_f32_16x16x32_bf16 v[26:29], v[170:173], v[150:153], v[26:29]
	s_cmp_eq_u32 s20, 16
	v_mfma_f32_16x16x32_bf16 v[10:13], v[170:173], v[154:157], v[10:13]
	global_load_lds_dwordx4 v[190:191], off
	v_mfma_f32_16x16x32_bf16 v[118:121], v[166:169], v[126:129], v[118:121]
	v_mfma_f32_16x16x32_bf16 v[102:105], v[166:169], v[130:133], v[102:105]
	v_mfma_f32_16x16x32_bf16 v[110:113], v[158:161], v[126:129], v[110:113]
	v_mfma_f32_16x16x32_bf16 v[94:97], v[158:161], v[130:133], v[94:97]
	v_mfma_f32_16x16x32_bf16 v[78:81], v[158:161], v[134:137], v[78:81]
	v_mfma_f32_16x16x32_bf16 v[62:65], v[158:161], v[138:141], v[62:65]
	v_mfma_f32_16x16x32_bf16 v[46:49], v[158:161], v[142:145], v[46:49]
	v_mfma_f32_16x16x32_bf16 v[30:33], v[158:161], v[146:149], v[30:33]
	v_mfma_f32_16x16x32_bf16 v[14:17], v[158:161], v[150:153], v[14:17]
	v_mfma_f32_16x16x32_bf16 v[2:5], v[158:161], v[154:157], v[2:5]
	v_add_u32_e32 v158, s23, v185
	v_add3_u32 v174, v158, v188, v187
	ds_read_b128 v[170:173], v174 offset:36864
	v_mfma_f32_16x16x32_bf16 v[86:89], v[166:169], v[134:137], v[86:89]
	s_mov_b32 s23, s20
	v_mfma_f32_16x16x32_bf16 v[70:73], v[166:169], v[138:141], v[70:73]
	v_mfma_f32_16x16x32_bf16 v[54:57], v[166:169], v[142:145], v[54:57]
	v_mfma_f32_16x16x32_bf16 v[38:41], v[166:169], v[146:149], v[38:41]
	v_mfma_f32_16x16x32_bf16 v[22:25], v[166:169], v[150:153], v[22:25]
	v_mfma_f32_16x16x32_bf16 v[6:9], v[166:169], v[154:157], v[6:9]
	v_add3_u32 v154, v158, v186, v187
	ds_read_b128 v[166:169], v174 offset:34816
	ds_read_b128 v[158:161], v174 offset:32768
	ds_read_b128 v[174:177], v174 offset:38912
	ds_read_b128 v[150:153], v154 offset:12288
	ds_read_b128 v[146:149], v154 offset:10240
	ds_read_b128 v[142:145], v154 offset:8192
	ds_read_b128 v[138:141], v154 offset:6144
	ds_read_b128 v[134:137], v154 offset:4096
	ds_read_b128 v[130:133], v154 offset:2048
	ds_read_b128 v[126:129], v154
	ds_read_b128 v[154:157], v154 offset:14336
	s_waitcnt lgkmcnt(0)
; DEVI void gemm16s(f32x4 (&acc)[4][8], const GUnit& cur, const GUnit& nxt, bool has_next, bool first, int& stg, bfu* lds) {
;     ...
; #pragma unroll 1
;     for (int kt = 0; kt < nkt; ++kt) {
;       G16_HEAD()
;       bf16x8 tf0[8], wf0[4];
;       G16_RD(tf0, wf0, 0)
;       ISSUE16(Ai, Bi, sAi, sBi, vAi, vBi, tk, st ^ 1);
;       G16_MM(tf0, wf0)
;       bf16x8 tf1[8], wf1[4];
;       G16_RD(tf1, wf1, 1)
;       G16_MM(tf1, wf1)
;       __builtin_amdgcn_sched_group_barrier(0x100, 12, 0);
; #pragma unroll
;       for (int i = 0; i < 8; ++i) {
;         __builtin_amdgcn_sched_group_barrier(0x008, 2, 0);
;         __builtin_amdgcn_sched_group_barrier(0x020, 1, 0);
;       }
; #pragma unroll
;       for (int i = 0; i < 12; ++i) {
;         __builtin_amdgcn_sched_group_barrier(0x008, 1, 0);
;         __builtin_amdgcn_sched_group_barrier(0x100, 1, 0);
;       }
;       __builtin_amdgcn_sched_group_barrier(0x008, 36, 0);
;       st ^= 1;
;     }
	v_mfma_f32_16x16x32_bf16 v[162:165], v[158:161], v[126:129], v[162:165]
	v_mfma_f32_16x16x32_bf16 v[114:117], v[158:161], v[130:133], v[114:117]
	v_mfma_f32_16x16x32_bf16 v[98:101], v[158:161], v[134:137], v[98:101]
	v_mfma_f32_16x16x32_bf16 v[82:85], v[158:161], v[138:141], v[82:85]
	v_mfma_f32_16x16x32_bf16 v[66:69], v[158:161], v[142:145], v[66:69]
	v_mfma_f32_16x16x32_bf16 v[50:53], v[158:161], v[146:149], v[50:53]
	v_mfma_f32_16x16x32_bf16 v[34:37], v[158:161], v[150:153], v[34:37]
	v_mfma_f32_16x16x32_bf16 v[18:21], v[158:161], v[154:157], v[18:21]
	v_mfma_f32_16x16x32_bf16 v[122:125], v[166:169], v[126:129], v[122:125]
	v_mfma_f32_16x16x32_bf16 v[106:109], v[166:169], v[130:133], v[106:109]
	v_mfma_f32_16x16x32_bf16 v[90:93], v[166:169], v[134:137], v[90:93]
	v_mfma_f32_16x16x32_bf16 v[74:77], v[166:169], v[138:141], v[74:77]
	v_mfma_f32_16x16x32_bf16 v[58:61], v[166:169], v[142:145], v[58:61]
	v_mfma_f32_16x16x32_bf16 v[42:45], v[166:169], v[146:149], v[42:45]
	v_mfma_f32_16x16x32_bf16 v[26:29], v[166:169], v[150:153], v[26:29]
	v_mfma_f32_16x16x32_bf16 v[10:13], v[166:169], v[154:157], v[10:13]
	v_mfma_f32_16x16x32_bf16 v[118:121], v[170:173], v[126:129], v[118:121]
	v_mfma_f32_16x16x32_bf16 v[102:105], v[170:173], v[130:133], v[102:105]
	v_mfma_f32_16x16x32_bf16 v[86:89], v[170:173], v[134:137], v[86:89]
	v_mfma_f32_16x16x32_bf16 v[70:73], v[170:173], v[138:141], v[70:73]
	v_mfma_f32_16x16x32_bf16 v[54:57], v[170:173], v[142:145], v[54:57]
	v_mfma_f32_16x16x32_bf16 v[38:41], v[170:173], v[146:149], v[38:41]
	v_mfma_f32_16x16x32_bf16 v[22:25], v[170:173], v[150:153], v[22:25]
	v_mfma_f32_16x16x32_bf16 v[6:9], v[170:173], v[154:157], v[6:9]
	v_mfma_f32_16x16x32_bf16 v[110:113], v[174:177], v[126:129], v[110:113]
	v_mfma_f32_16x16x32_bf16 v[94:97], v[174:177], v[130:133], v[94:97]
	v_mfma_f32_16x16x32_bf16 v[78:81], v[174:177], v[134:137], v[78:81]
	v_mfma_f32_16x16x32_bf16 v[62:65], v[174:177], v[138:141], v[62:65]
	v_mfma_f32_16x16x32_bf16 v[46:49], v[174:177], v[142:145], v[46:49]
	v_mfma_f32_16x16x32_bf16 v[30:33], v[174:177], v[146:149], v[30:33]
	v_mfma_f32_16x16x32_bf16 v[14:17], v[174:177], v[150:153], v[14:17]
	v_mfma_f32_16x16x32_bf16 v[2:5], v[174:177], v[154:157], v[2:5]
	s_cbranch_scc0 .LBB0_245
	s_mov_b32 s20, s54
	s_mov_b32 s54, s20
	s_andn2_b64 vcc, exec, s[44:45]
	s_cbranch_vccz .LBB0_239
	s_branch .LBB0_240

; DEVI void gemm16s(f32x4 (&acc)[4][8], const GUnit& cur, const GUnit& nxt, bool has_next, bool first, int& stg, bfu* lds) {
;     ...
; #pragma unroll 1
;     for (int kt = 0; kt < nkt; ++kt) {
;       G16_HEAD()
;       bf16x8 tf0[8], wf0[4];
;       G16_RD(tf0, wf0, 0)
;       ISSUE16(Ai, Bi, sAi, sBi, vAi, vBi, tk, st ^ 1);
;       G16_MM(tf0, wf0)
;       bf16x8 tf1[8], wf1[4];
;       G16_RD(tf1, wf1, 1)
;       G16_MM(tf1, wf1)
;       __builtin_amdgcn_sched_group_barrier(0x100, 12, 0);
; #pragma unroll
;       for (int i = 0; i < 8; ++i) {
;         __builtin_amdgcn_sched_group_barrier(0x008, 2, 0);
;         __builtin_amdgcn_sched_group_barrier(0x020, 1, 0);
;       }
; #pragma unroll
;       for (int i = 0; i < 12; ++i) {
;         __builtin_amdgcn_sched_group_barrier(0x008, 1, 0);
;         __builtin_amdgcn_sched_group_barrier(0x100, 1, 0);
;       }
;       __builtin_amdgcn_sched_group_barrier(0x008, 36, 0);
;       st ^= 1;
;     }
.LBB0_760:
	s_setprio 1
	s_add_i32 s20, s23, 1
	s_cmp_gt_u32 s23, 14
	s_cselect_b64 s[36:37], -1, 0
	s_and_b64 s[58:59], s[36:37], exec
	s_cselect_b32 s30, s56, s20
	s_and_b64 s[36:37], s[0:1], s[36:37]
	s_and_b64 s[58:59], s[36:37], exec
	s_cselect_b32 s57, s29, s41
	s_cselect_b32 s58, s28, s40
	s_lshl_b32 s23, s50, 16
	s_addk_i32 s23, 0xc20
	v_add_u32_e32 v154, s23, v187
	s_waitcnt vmcnt(0)
	v_add3_u32 v146, v154, v189, v190
	v_add3_u32 v154, v154, v191, v190
	s_waitcnt lgkmcnt(0)
	s_barrier
	ds_read_b128 v[174:177], v154 offset:32768
	s_and_b64 s[36:37], s[36:37], exec
	s_cselect_b32 s60, s55, s45
	s_cselect_b32 s61, s54, s44
	s_xor_b32 s50, s50, 1
	ds_read_b128 v[114:117], v146
	ds_read_b128 v[118:121], v146 offset:2048
	s_lshl_b32 s36, s50, 16
	ds_read_b128 v[122:125], v146 offset:4096
	ds_read_b128 v[126:129], v146 offset:6144
	s_add_i32 s62, s27, s36
	s_lshl_b64 s[36:37], s[30:31], 7
	ds_read_b128 v[134:137], v146 offset:8192
	ds_read_b128 v[138:141], v146 offset:10240
	ds_read_b128 v[170:173], v154 offset:34816
	s_add_u32 s58, s58, s36
	s_addc_u32 s59, s57, s37
	v_lshl_add_u64 v[192:193], s[58:59], 0, v[184:185]
	s_mov_b32 m0, s62
	ds_read_b128 v[142:145], v146 offset:12288
	ds_read_b128 v[146:149], v146 offset:14336
	ds_read_b128 v[166:169], v154 offset:36864
	ds_read_b128 v[154:157], v154 offset:38912
	v_lshl_add_u64 v[194:195], v[192:193], 0, s[14:15]
	s_waitcnt lgkmcnt(0)
	v_mfma_f32_16x16x32_bf16 v[162:165], v[174:177], v[114:117], v[162:165]
	v_mfma_f32_16x16x32_bf16 v[158:161], v[174:177], v[118:121], v[158:161]
	global_load_lds_dwordx4 v[192:193], off
	s_add_i32 m0, s62, 0x2000
	v_mfma_f32_16x16x32_bf16 v[150:153], v[174:177], v[122:125], v[150:153]
	v_mfma_f32_16x16x32_bf16 v[130:133], v[174:177], v[126:129], v[130:133]
	global_load_lds_dwordx4 v[194:195], off
	v_lshl_add_u64 v[194:195], v[192:193], 0, s[8:9]
	s_add_i32 m0, s62, 0x4000
	v_mfma_f32_16x16x32_bf16 v[110:113], v[174:177], v[134:137], v[110:113]
	v_lshl_add_u64 v[192:193], v[192:193], 0, s[34:35]
	v_mfma_f32_16x16x32_bf16 v[106:109], v[174:177], v[138:141], v[106:109]
	global_load_lds_dwordx4 v[194:195], off
	s_add_i32 m0, s62, 0x6000
	s_add_u32 s36, s61, s36
	s_addc_u32 s37, s60, s37
	v_mfma_f32_16x16x32_bf16 v[82:85], v[174:177], v[142:145], v[82:85]
	v_mfma_f32_16x16x32_bf16 v[58:61], v[174:177], v[146:149], v[58:61]
	global_load_lds_dwordx4 v[192:193], off
	v_lshl_add_u64 v[192:193], s[36:37], 0, v[184:185]
	s_add_i32 m0, s62, 0x8000
	v_lshl_add_u64 v[194:195], v[192:193], 0, s[14:15]
	v_mfma_f32_16x16x32_bf16 v[102:105], v[170:173], v[114:117], v[102:105]
	v_mfma_f32_16x16x32_bf16 v[98:101], v[170:173], v[118:121], v[98:101]
	global_load_lds_dwordx4 v[192:193], off
	s_add_i32 m0, s62, 0xa000
	v_mfma_f32_16x16x32_bf16 v[94:97], v[170:173], v[122:125], v[94:97]
	v_mfma_f32_16x16x32_bf16 v[90:93], v[170:173], v[126:129], v[90:93]
	global_load_lds_dwordx4 v[194:195], off
	v_lshl_add_u64 v[194:195], v[192:193], 0, s[8:9]
	s_add_i32 m0, s62, 0xc000
	v_lshl_add_u64 v[192:193], v[192:193], 0, s[34:35]
	v_mfma_f32_16x16x32_bf16 v[86:89], v[170:173], v[134:137], v[86:89]
	v_mfma_f32_16x16x32_bf16 v[78:81], v[170:173], v[138:141], v[78:81]
	global_load_lds_dwordx4 v[194:195], off
	s_add_i32 m0, s62, 0xe000
	v_mfma_f32_16x16x32_bf16 v[46:49], v[170:173], v[142:145], v[46:49]
	s_cmp_eq_u32 s20, 16
	v_mfma_f32_16x16x32_bf16 v[14:17], v[170:173], v[146:149], v[14:17]
	global_load_lds_dwordx4 v[192:193], off
	v_mfma_f32_16x16x32_bf16 v[74:77], v[166:169], v[114:117], v[74:77]
	v_mfma_f32_16x16x32_bf16 v[70:73], v[166:169], v[118:121], v[70:73]
	v_mfma_f32_16x16x32_bf16 v[42:45], v[154:157], v[114:117], v[42:45]
	v_mfma_f32_16x16x32_bf16 v[38:41], v[154:157], v[118:121], v[38:41]
	v_mfma_f32_16x16x32_bf16 v[34:37], v[154:157], v[122:125], v[34:37]
	v_mfma_f32_16x16x32_bf16 v[30:33], v[154:157], v[126:129], v[30:33]
	v_mfma_f32_16x16x32_bf16 v[26:29], v[154:157], v[134:137], v[26:29]
	v_mfma_f32_16x16x32_bf16 v[18:21], v[154:157], v[138:141], v[18:21]
	v_mfma_f32_16x16x32_bf16 v[10:13], v[154:157], v[142:145], v[10:13]
	v_mfma_f32_16x16x32_bf16 v[2:5], v[154:157], v[146:149], v[2:5]
	v_add_u32_e32 v154, s23, v188
	v_add3_u32 v174, v154, v191, v190
	ds_read_b128 v[170:173], v174 offset:36864
	v_mfma_f32_16x16x32_bf16 v[66:69], v[166:169], v[122:125], v[66:69]
	s_mov_b32 s23, s20
	v_mfma_f32_16x16x32_bf16 v[62:65], v[166:169], v[126:129], v[62:65]
	v_mfma_f32_16x16x32_bf16 v[54:57], v[166:169], v[134:137], v[54:57]
	v_mfma_f32_16x16x32_bf16 v[50:53], v[166:169], v[138:141], v[50:53]
	v_mfma_f32_16x16x32_bf16 v[22:25], v[166:169], v[142:145], v[22:25]
	v_mfma_f32_16x16x32_bf16 v[6:9], v[166:169], v[146:149], v[6:9]
	v_add3_u32 v146, v154, v189, v190
	ds_read_b128 v[166:169], v174 offset:34816
	ds_read_b128 v[154:157], v174 offset:32768
	ds_read_b128 v[174:177], v174 offset:38912
	ds_read_b128 v[142:145], v146 offset:12288
	ds_read_b128 v[138:141], v146 offset:10240
	ds_read_b128 v[134:137], v146 offset:8192
	ds_read_b128 v[126:129], v146 offset:6144
	ds_read_b128 v[122:125], v146 offset:4096
	ds_read_b128 v[118:121], v146 offset:2048
	ds_read_b128 v[114:117], v146
	ds_read_b128 v[146:149], v146 offset:14336
	s_waitcnt lgkmcnt(0)
; DEVI void gemm16s(f32x4 (&acc)[4][8], const GUnit& cur, const GUnit& nxt, bool has_next, bool first, int& stg, bfu* lds) {
;     ...
; #pragma unroll 1
;     for (int kt = 0; kt < nkt; ++kt) {
;       G16_HEAD()
;       bf16x8 tf0[8], wf0[4];
;       G16_RD(tf0, wf0, 0)
;       ISSUE16(Ai, Bi, sAi, sBi, vAi, vBi, tk, st ^ 1);
;       G16_MM(tf0, wf0)
;       bf16x8 tf1[8], wf1[4];
;       G16_RD(tf1, wf1, 1)
;       G16_MM(tf1, wf1)
;       __builtin_amdgcn_sched_group_barrier(0x100, 12, 0);
; #pragma unroll
;       for (int i = 0; i < 8; ++i) {
;         __builtin_amdgcn_sched_group_barrier(0x008, 2, 0);
;         __builtin_amdgcn_sched_group_barrier(0x020, 1, 0);
;       }
; #pragma unroll
;       for (int i = 0; i < 12; ++i) {
;         __builtin_amdgcn_sched_group_barrier(0x008, 1, 0);
;         __builtin_amdgcn_sched_group_barrier(0x100, 1, 0);
;       }
;       __builtin_amdgcn_sched_group_barrier(0x008, 36, 0);
;       st ^= 1;
;     }
	v_mfma_f32_16x16x32_bf16 v[162:165], v[154:157], v[114:117], v[162:165]
	v_mfma_f32_16x16x32_bf16 v[158:161], v[154:157], v[118:121], v[158:161]
	v_mfma_f32_16x16x32_bf16 v[150:153], v[154:157], v[122:125], v[150:153]
	v_mfma_f32_16x16x32_bf16 v[130:133], v[154:157], v[126:129], v[130:133]
	v_mfma_f32_16x16x32_bf16 v[110:113], v[154:157], v[134:137], v[110:113]
	v_mfma_f32_16x16x32_bf16 v[106:109], v[154:157], v[138:141], v[106:109]
	v_mfma_f32_16x16x32_bf16 v[82:85], v[154:157], v[142:145], v[82:85]
	v_mfma_f32_16x16x32_bf16 v[58:61], v[154:157], v[146:149], v[58:61]
	v_mfma_f32_16x16x32_bf16 v[102:105], v[166:169], v[114:117], v[102:105]
	v_mfma_f32_16x16x32_bf16 v[98:101], v[166:169], v[118:121], v[98:101]
	v_mfma_f32_16x16x32_bf16 v[94:97], v[166:169], v[122:125], v[94:97]
	v_mfma_f32_16x16x32_bf16 v[90:93], v[166:169], v[126:129], v[90:93]
	v_mfma_f32_16x16x32_bf16 v[86:89], v[166:169], v[134:137], v[86:89]
	v_mfma_f32_16x16x32_bf16 v[78:81], v[166:169], v[138:141], v[78:81]
	v_mfma_f32_16x16x32_bf16 v[46:49], v[166:169], v[142:145], v[46:49]
	v_mfma_f32_16x16x32_bf16 v[14:17], v[166:169], v[146:149], v[14:17]
	v_mfma_f32_16x16x32_bf16 v[74:77], v[170:173], v[114:117], v[74:77]
	v_mfma_f32_16x16x32_bf16 v[70:73], v[170:173], v[118:121], v[70:73]
	v_mfma_f32_16x16x32_bf16 v[66:69], v[170:173], v[122:125], v[66:69]
	v_mfma_f32_16x16x32_bf16 v[62:65], v[170:173], v[126:129], v[62:65]
	v_mfma_f32_16x16x32_bf16 v[54:57], v[170:173], v[134:137], v[54:57]
	v_mfma_f32_16x16x32_bf16 v[50:53], v[170:173], v[138:141], v[50:53]
	v_mfma_f32_16x16x32_bf16 v[22:25], v[170:173], v[142:145], v[22:25]
	v_mfma_f32_16x16x32_bf16 v[6:9], v[170:173], v[146:149], v[6:9]
	v_mfma_f32_16x16x32_bf16 v[42:45], v[174:177], v[114:117], v[42:45]
	v_mfma_f32_16x16x32_bf16 v[38:41], v[174:177], v[118:121], v[38:41]
	v_mfma_f32_16x16x32_bf16 v[34:37], v[174:177], v[122:125], v[34:37]
	v_mfma_f32_16x16x32_bf16 v[30:33], v[174:177], v[126:129], v[30:33]
	v_mfma_f32_16x16x32_bf16 v[26:29], v[174:177], v[134:137], v[26:29]
	v_mfma_f32_16x16x32_bf16 v[18:21], v[174:177], v[138:141], v[18:21]
	v_mfma_f32_16x16x32_bf16 v[10:13], v[174:177], v[142:145], v[10:13]
	v_mfma_f32_16x16x32_bf16 v[2:5], v[174:177], v[146:149], v[2:5]
	s_cbranch_scc0 .LBB0_760
	s_mov_b32 s20, s50
	s_mov_b32 s50, s20
	s_andn2_b64 vcc, exec, s[42:43]
	s_cbranch_vccz .LBB0_688
	s_branch .LBB0_689
